# attention QK^T: K-fragment ds_reads pipelined 6 deep with counted lgkmcnt (plus pool edit)
# baseline (speedup 1.0000x reference)
.LBB0_480:
	s_cmp_le_u32 s73, s70
	s_cselect_b64 s[38:39], -1, 0
	s_cmp_gt_u32 s73, s70
	s_cbranch_scc1 .LBB0_486
	s_and_b32 s4, s36, 0x4000
	v_add_u32_e32 v229, s4, v199
	v_add_u32_e32 v246, v229, v214
	v_add_u32_e32 v247, v229, v215
	v_add_u32_e32 v248, v229, v216
	v_add_u32_e32 v249, v229, v217
	s_add_i32 s4, s73, 63
	s_cmp_le_u32 s4, s68
	ds_read_b128 v[230:233], v246
	ds_read_b128 v[234:237], v247
	ds_read_b128 v[238:241], v248
	ds_read_b128 v[242:245], v249
	ds_read_b128 v[184:187], v246 offset:4096
	ds_read_b128 v[188:191], v247 offset:4096
	s_waitcnt lgkmcnt(5)
	v_mfma_f32_16x16x32_bf16 v[164:167], v[230:233], v[36:39], 0
	v_mfma_f32_16x16x32_bf16 v[160:163], v[230:233], v[56:59], 0
	ds_read_b128 v[230:233], v248 offset:4096
	s_waitcnt lgkmcnt(5)
	v_mfma_f32_16x16x32_bf16 v[164:167], v[234:237], v[44:47], v[164:167]
	v_mfma_f32_16x16x32_bf16 v[160:163], v[234:237], v[60:63], v[160:163]
	ds_read_b128 v[234:237], v249 offset:4096
	s_waitcnt lgkmcnt(5)
	v_mfma_f32_16x16x32_bf16 v[164:167], v[238:241], v[48:51], v[164:167]
	v_mfma_f32_16x16x32_bf16 v[160:163], v[238:241], v[64:67], v[160:163]
	ds_read_b128 v[238:241], v246 offset:8192
	s_waitcnt lgkmcnt(5)
	v_mfma_f32_16x16x32_bf16 v[164:167], v[242:245], v[52:55], v[164:167]
	v_mfma_f32_16x16x32_bf16 v[160:163], v[242:245], v[68:71], v[160:163]
	ds_read_b128 v[242:245], v247 offset:8192
	s_waitcnt lgkmcnt(5)
	v_mfma_f32_16x16x32_bf16 v[180:183], v[184:187], v[36:39], 0
	v_mfma_f32_16x16x32_bf16 v[172:175], v[184:187], v[56:59], 0
	ds_read_b128 v[184:187], v248 offset:8192
	s_waitcnt lgkmcnt(5)
	v_mfma_f32_16x16x32_bf16 v[180:183], v[188:191], v[44:47], v[180:183]
	v_mfma_f32_16x16x32_bf16 v[172:175], v[188:191], v[60:63], v[172:175]
	ds_read_b128 v[188:191], v249 offset:8192
	s_waitcnt lgkmcnt(5)
	v_mfma_f32_16x16x32_bf16 v[180:183], v[230:233], v[48:51], v[180:183]
	v_mfma_f32_16x16x32_bf16 v[172:175], v[230:233], v[64:67], v[172:175]
	ds_read_b128 v[230:233], v246 offset:12288
	s_waitcnt lgkmcnt(5)
	v_mfma_f32_16x16x32_bf16 v[180:183], v[234:237], v[52:55], v[180:183]
	v_mfma_f32_16x16x32_bf16 v[172:175], v[234:237], v[68:71], v[172:175]
	ds_read_b128 v[234:237], v247 offset:12288
	s_waitcnt lgkmcnt(5)
	v_mfma_f32_16x16x32_bf16 v[176:179], v[238:241], v[36:39], 0
	v_mfma_f32_16x16x32_bf16 v[168:171], v[238:241], v[56:59], 0
	ds_read_b128 v[238:241], v248 offset:12288
	s_waitcnt lgkmcnt(5)
	v_mfma_f32_16x16x32_bf16 v[176:179], v[242:245], v[44:47], v[176:179]
	v_mfma_f32_16x16x32_bf16 v[168:171], v[242:245], v[60:63], v[168:171]
	ds_read_b128 v[242:245], v249 offset:12288
	s_waitcnt lgkmcnt(5)
	v_mfma_f32_16x16x32_bf16 v[176:179], v[184:187], v[48:51], v[176:179]
	v_mfma_f32_16x16x32_bf16 v[168:171], v[184:187], v[64:67], v[168:171]
	s_waitcnt lgkmcnt(4)
	v_mfma_f32_16x16x32_bf16 v[176:179], v[188:191], v[52:55], v[176:179]
	v_mfma_f32_16x16x32_bf16 v[168:171], v[188:191], v[68:71], v[168:171]
	s_waitcnt lgkmcnt(3)
	v_mfma_f32_16x16x32_bf16 v[188:191], v[230:233], v[36:39], 0
	v_mfma_f32_16x16x32_bf16 v[184:187], v[230:233], v[56:59], 0
	s_waitcnt lgkmcnt(2)
	v_mfma_f32_16x16x32_bf16 v[188:191], v[234:237], v[44:47], v[188:191]
	v_mfma_f32_16x16x32_bf16 v[184:187], v[234:237], v[60:63], v[184:187]
	s_waitcnt lgkmcnt(1)
	v_mfma_f32_16x16x32_bf16 v[188:191], v[238:241], v[48:51], v[188:191]
	v_mfma_f32_16x16x32_bf16 v[184:187], v[238:241], v[64:67], v[184:187]
	s_waitcnt lgkmcnt(0)
	v_mfma_f32_16x16x32_bf16 v[188:191], v[242:245], v[52:55], v[188:191]
	v_mfma_f32_16x16x32_bf16 v[184:187], v[242:245], v[68:71], v[184:187]
	s_cbranch_scc1 .LBB0_483
	v_add_u32_e32 v229, s73, v198
	v_mov_b32_e32 v230, s61
	v_cmp_gt_i32_e32 vcc, v229, v192
	v_cmp_lt_i32_e64 s[4:5], v229, v192
	v_add_u32_e32 v231, 2, v229
	v_cndmask_b32_e32 v230, v164, v230, vcc
	v_cndmask_b32_e64 v164, v230, v164, s[4:5]
	v_cndmask_b32_e64 v165, v212, v165, s[4:5]
	v_cmp_le_i32_e64 s[4:5], v231, v192
	v_add_u32_e32 v232, 3, v229
	v_mov_b32_e32 v230, s61
	v_cndmask_b32_e64 v166, v212, v166, s[4:5]
	v_cmp_le_i32_e64 s[4:5], v232, v192
	v_add_u32_e32 v233, 17, v229
	v_add_u32_e32 v234, 18, v229
	v_cndmask_b32_e64 v167, v212, v167, s[4:5]
	v_cmp_gt_i32_e64 s[4:5], v229, v226
	v_add_u32_e32 v235, 19, v229
	v_add_u32_e32 v236, 32, v229
	v_cndmask_b32_e64 v180, v180, v230, s[4:5]
	v_cmp_le_i32_e64 s[4:5], v233, v192
	v_add_u32_e32 v237, 33, v229
	v_add_u32_e32 v238, 34, v229
	v_cndmask_b32_e64 v181, v212, v181, s[4:5]
	v_cmp_le_i32_e64 s[4:5], v234, v192
	v_add_u32_e32 v239, 35, v229
	v_add_u32_e32 v240, 48, v229
	v_cndmask_b32_e64 v182, v212, v182, s[4:5]
	v_cmp_le_i32_e64 s[4:5], v235, v192
	v_add_u32_e32 v241, 49, v229
	v_add_u32_e32 v242, 50, v229
	v_cndmask_b32_e64 v183, v212, v183, s[4:5]
	v_cmp_gt_i32_e64 s[4:5], v236, v192
	v_add_u32_e32 v243, 51, v229
	s_nop 0
	v_cndmask_b32_e64 v176, v176, v230, s[4:5]
	v_cmp_le_i32_e64 s[4:5], v237, v192
	s_nop 1
	v_cndmask_b32_e64 v177, v212, v177, s[4:5]
	v_cmp_le_i32_e64 s[4:5], v238, v192
	s_nop 1
	v_cndmask_b32_e64 v178, v212, v178, s[4:5]
	v_cmp_le_i32_e64 s[4:5], v239, v192
	s_nop 1
	v_cndmask_b32_e64 v179, v212, v179, s[4:5]
	v_cmp_gt_i32_e64 s[4:5], v240, v192
	s_nop 1
	v_cndmask_b32_e64 v188, v188, v230, s[4:5]
	v_cmp_le_i32_e64 s[4:5], v241, v192
	s_nop 1
	v_cndmask_b32_e64 v189, v212, v189, s[4:5]
	v_cmp_le_i32_e64 s[4:5], v242, v192
	s_nop 1
	v_cndmask_b32_e64 v190, v212, v190, s[4:5]
	v_cmp_le_i32_e64 s[4:5], v243, v192
	s_nop 1
	v_cndmask_b32_e64 v191, v212, v191, s[4:5]
	v_cmp_gt_i32_e64 s[4:5], v229, v194
	s_nop 1
	v_cndmask_b32_e64 v230, v160, v230, s[4:5]
	v_cmp_lt_i32_e64 s[4:5], v229, v194
	s_nop 1
	v_cndmask_b32_e64 v160, v230, v160, s[4:5]
	v_mov_b32_e32 v230, s61
	v_cndmask_b32_e32 v172, v172, v230, vcc
	v_cmp_le_i32_e32 vcc, v233, v194
	v_cndmask_b32_e64 v161, v212, v161, s[4:5]
	v_cmp_le_i32_e64 s[4:5], v231, v194
	v_cndmask_b32_e32 v173, v212, v173, vcc
	v_cmp_le_i32_e32 vcc, v234, v194
	v_cndmask_b32_e64 v162, v212, v162, s[4:5]
	v_cmp_le_i32_e64 s[4:5], v232, v194
	v_cndmask_b32_e32 v174, v212, v174, vcc
	v_cmp_le_i32_e32 vcc, v235, v194
	v_cndmask_b32_e64 v163, v212, v163, s[4:5]
	s_nop 0
	v_cndmask_b32_e32 v175, v212, v175, vcc
	v_cmp_gt_i32_e32 vcc, v236, v194
	s_nop 1
	v_cndmask_b32_e32 v168, v168, v230, vcc
	v_cmp_le_i32_e32 vcc, v237, v194
	s_nop 1
	v_cndmask_b32_e32 v169, v212, v169, vcc
	v_cmp_le_i32_e32 vcc, v238, v194
	s_nop 1
	v_cndmask_b32_e32 v170, v212, v170, vcc
	v_cmp_le_i32_e32 vcc, v239, v194
	s_nop 1
	v_cndmask_b32_e32 v171, v212, v171, vcc
	v_cmp_gt_i32_e32 vcc, v240, v194
	s_nop 1
	v_cndmask_b32_e32 v184, v184, v230, vcc
	v_cmp_le_i32_e32 vcc, v241, v194
	s_nop 1
	v_cndmask_b32_e32 v185, v212, v185, vcc
	v_cmp_le_i32_e32 vcc, v242, v194
	s_nop 1
	v_cndmask_b32_e32 v186, v212, v186, vcc
	v_cmp_le_i32_e32 vcc, v243, v194
	s_nop 1
	v_cndmask_b32_e32 v187, v212, v187, vcc
